# phase 0: the 16 global loads of each transpose tile / GEMV iteration / Fourier-fold tile are issued together instead of one exposed round trip each
# speedup vs baseline: 1.1635x; 1.0209x over previous
; #define TIDX tid_opaque()
; DI void transpose_tile4(const float* src, int lds_, half_t* dst, int ldd, float* tile) {
;   const int tid = TIDX;
;   {
;     const int k0 = tid >> 6, c4 = tid & 63;
;     const float* sp = src + (size_t)k0 * lds_ + c4 * 4;
;     float* tp = tile + (c4 >> 4) * 4352 + k0 * 68 + (c4 & 15) * 4;
; #pragma unroll
;     for (int i = 0; i < 16; i++) *(float4*)(tp + i * 4 * 68) = *(const float4*)(sp + (size_t)i * 4 * lds_);
;   }
;   __syncthreads();
; #pragma unroll
;   for (int i = 0; i < 8; i++) {
;     int idx = i * 256 + tid, j = idx >> 9, r = idx & 511, kc = r >> 6, n = r & 63;
;     const float* t = tile + j * 4352 + kc * 8 * 68 + n;
;     h8 o;
; #pragma unroll
;     for (int u = 0; u < 8; u++) o[u] = (half_t)t[u * 68];
;     *(h8*)(dst + (size_t)(j * 64 + n) * ldd + kc * 8) = o;
;   }
;   __syncthreads();
.LBB0_5:
	v_mov_b32_e32 v7, v172
	v_ashrrev_i32_e32 v69, 6, v7
	v_mad_u64_u32 v[8:9], s[28:29], v69, s50, 0
	v_ashrrev_i32_e32 v71, 31, v69
	v_mov_b32_e32 v20, v9
	v_mad_u64_u32 v[92:93], s[28:29], v71, s50, v[20:21]
	v_and_b32_e32 v6, 63, v7
	v_mov_b32_e32 v9, v92
	v_lshl_add_u64 v[92:93], v[8:9], 2, s[48:49]
	v_lshlrev_b32_e32 v20, 4, v6
	v_lshl_add_u64 v[96:97], v[92:93], 0, v[20:21]
	global_load_dwordx4 a[0:3], v[96:97], off
	s_mul_i32 s78, s50, 4
	v_lshl_add_u64 v[92:93], s[78:79], 2, v[96:97]
	global_load_dwordx4 a[4:7], v[92:93], off
	s_mul_i32 s78, s50, 8
	v_lshl_add_u64 v[92:93], s[78:79], 2, v[96:97]
	global_load_dwordx4 a[8:11], v[92:93], off
	s_mul_i32 s78, s50, 12
	v_lshl_add_u64 v[92:93], s[78:79], 2, v[96:97]
	global_load_dwordx4 a[12:15], v[92:93], off
	s_mul_i32 s78, s50, 16
	v_lshl_add_u64 v[92:93], s[78:79], 2, v[96:97]
	global_load_dwordx4 a[16:19], v[92:93], off
	s_mul_i32 s78, s50, 20
	v_lshl_add_u64 v[92:93], s[78:79], 2, v[96:97]
	global_load_dwordx4 a[20:23], v[92:93], off
	s_mul_i32 s78, s50, 24
	v_lshl_add_u64 v[92:93], s[78:79], 2, v[96:97]
	global_load_dwordx4 a[24:27], v[92:93], off
	s_mul_i32 s78, s50, 28
	v_lshl_add_u64 v[92:93], s[78:79], 2, v[96:97]
	global_load_dwordx4 a[28:31], v[92:93], off
	s_mul_i32 s78, s50, 32
	v_lshl_add_u64 v[92:93], s[78:79], 2, v[96:97]
	global_load_dwordx4 a[32:35], v[92:93], off
	s_mul_i32 s78, s50, 36
	v_lshl_add_u64 v[92:93], s[78:79], 2, v[96:97]
	global_load_dwordx4 a[36:39], v[92:93], off
	s_mul_i32 s78, s50, 40
	v_lshl_add_u64 v[92:93], s[78:79], 2, v[96:97]
	global_load_dwordx4 a[40:43], v[92:93], off
	s_mul_i32 s78, s50, 44
	v_lshl_add_u64 v[92:93], s[78:79], 2, v[96:97]
	global_load_dwordx4 a[44:47], v[92:93], off
	s_mul_i32 s78, s50, 48
	v_lshl_add_u64 v[92:93], s[78:79], 2, v[96:97]
	global_load_dwordx4 a[48:51], v[92:93], off
	s_mul_i32 s78, s50, 52
	v_lshl_add_u64 v[92:93], s[78:79], 2, v[96:97]
	global_load_dwordx4 a[52:55], v[92:93], off
	s_mul_i32 s78, s50, 56
	v_lshl_add_u64 v[92:93], s[78:79], 2, v[96:97]
	global_load_dwordx4 a[56:59], v[92:93], off
	s_mul_i32 s78, s50, 60
	v_lshl_add_u64 v[92:93], s[78:79], 2, v[96:97]
	global_load_dwordx4 a[60:63], v[92:93], off
	s_movk_i32 s28, 0x110
	v_bfe_u32 v9, v7, 4, 2
	v_mul_lo_u32 v20, v69, s28
	v_lshlrev_b32_e32 v69, 4, v7
	v_mul_u32_u24_e32 v9, 0x4400, v9
	v_and_b32_e32 v69, 0xf0, v69
	v_add3_u32 v9, v9, v20, v69
	v_lshrrev_b32_e32 v69, 3, v7
	v_and_b32_e32 v69, 56, v69
	v_lshlrev_b32_e32 v8, 2, v6
	v_mul_u32_u24_e32 v71, 0x110, v69
	s_waitcnt vmcnt(15)
	ds_write_b128 v9, a[0:3]
	s_waitcnt vmcnt(14)
	ds_write_b128 v9, a[4:7] offset:1088
	s_waitcnt vmcnt(13)
	ds_write_b128 v9, a[8:11] offset:2176
	s_waitcnt vmcnt(12)
	ds_write_b128 v9, a[12:15] offset:3264
	s_waitcnt vmcnt(11)
	ds_write_b128 v9, a[16:19] offset:4352
	s_waitcnt vmcnt(10)
	ds_write_b128 v9, a[20:23] offset:5440
	s_waitcnt vmcnt(9)
	ds_write_b128 v9, a[24:27] offset:6528
	s_waitcnt vmcnt(8)
	ds_write_b128 v9, a[28:31] offset:7616
	s_waitcnt vmcnt(7)
	ds_write_b128 v9, a[32:35] offset:8704
	s_waitcnt vmcnt(6)
	ds_write_b128 v9, a[36:39] offset:9792
	s_waitcnt vmcnt(5)
	ds_write_b128 v9, a[40:43] offset:10880
	s_waitcnt vmcnt(4)
	ds_write_b128 v9, a[44:47] offset:11968
	s_waitcnt vmcnt(3)
	ds_write_b128 v9, a[48:51] offset:13056
	s_waitcnt vmcnt(2)
	ds_write_b128 v9, a[52:55] offset:14144
	s_waitcnt vmcnt(1)
	ds_write_b128 v9, a[56:59] offset:15232
	s_waitcnt vmcnt(0)
	ds_write_b128 v9, a[60:63] offset:16320
	v_ashrrev_i32_e32 v9, 9, v7
	v_mul_i32_i24_e32 v20, 0x4400, v9
	v_add3_u32 v20, v20, v71, v8
	s_waitcnt lgkmcnt(0)
	s_barrier
	ds_read2_b32 v[96:97], v20 offset1:68
	ds_read2_b32 v[92:93], v20 offset0:136 offset1:204
	v_add_u32_e32 v20, 0x400, v20
	ds_read2_b32 v[98:99], v20 offset0:16 offset1:84
	ds_read2_b32 v[94:95], v20 offset0:152 offset1:220
	v_lshl_or_b32 v20, v9, 6, v6
	v_ashrrev_i32_e32 v9, 31, v9
	s_waitcnt lgkmcnt(2)
	v_cvt_pk_f16_f32 v93, v92, v93
	v_cvt_pk_f16_f32 v92, v96, v97
	v_mul_lo_u32 v73, s47, v20
	v_mul_lo_u32 v9, s46, v9
	v_mad_u64_u32 v[96:97], s[28:29], s46, v20, 0
	v_add3_u32 v97, v97, v9, v73
	v_add_u32_e32 v9, 0x100, v7
	v_lshlrev_b32_e32 v20, 1, v69
	v_ashrrev_i32_e32 v69, 9, v9
	v_lshrrev_b32_e32 v9, 3, v9
	v_lshl_add_u64 v[96:97], v[96:97], 1, s[0:1]
	v_and_b32_e32 v9, 56, v9
	s_waitcnt lgkmcnt(0)
	v_cvt_pk_f16_f32 v95, v94, v95
	v_cvt_pk_f16_f32 v94, v98, v99
	v_lshl_add_u64 v[96:97], v[96:97], 0, v[20:21]
	v_mul_i32_i24_e32 v73, 0x4400, v69
	v_mul_u32_u24_e32 v75, 0x110, v9
	global_store_dwordx4 v[96:97], v[92:95], off
	v_add3_u32 v73, v73, v75, v8
	ds_read2_b32 v[96:97], v73 offset1:68
	ds_read2_b32 v[92:93], v73 offset0:136 offset1:204
	v_add_u32_e32 v73, 0x400, v73
	ds_read2_b32 v[98:99], v73 offset0:16 offset1:84
	ds_read2_b32 v[94:95], v73 offset0:152 offset1:220
	v_lshl_or_b32 v73, v69, 6, v6
	v_ashrrev_i32_e32 v69, 31, v69
	s_waitcnt lgkmcnt(2)
	v_cvt_pk_f16_f32 v93, v92, v93
	v_cvt_pk_f16_f32 v92, v96, v97
	v_mul_lo_u32 v75, s47, v73
	v_mul_lo_u32 v69, s46, v69
	v_mad_u64_u32 v[96:97], s[28:29], s46, v73, 0
	s_waitcnt lgkmcnt(0)
	v_cvt_pk_f16_f32 v95, v94, v95
	v_cvt_pk_f16_f32 v94, v98, v99
	v_add3_u32 v97, v97, v69, v75
	v_lshlrev_b32_e32 v98, 1, v9
	v_add_u32_e32 v9, 0x200, v7
	v_lshl_add_u64 v[96:97], v[96:97], 1, s[0:1]
	v_mov_b32_e32 v99, v21
	v_ashrrev_i32_e32 v9, 9, v9
	v_lshl_add_u64 v[96:97], v[96:97], 0, v[98:99]
	v_mul_i32_i24_e32 v69, 0x4400, v9
	global_store_dwordx4 v[96:97], v[92:95], off
	v_add3_u32 v69, v69, v71, v8
	ds_read2_b32 v[96:97], v69 offset1:68
	ds_read2_b32 v[92:93], v69 offset0:136 offset1:204
	v_add_u32_e32 v69, 0x400, v69
	ds_read2_b32 v[98:99], v69 offset0:16 offset1:84
	ds_read2_b32 v[94:95], v69 offset0:152 offset1:220
	v_lshl_or_b32 v69, v9, 6, v6
	v_ashrrev_i32_e32 v9, 31, v9
	s_waitcnt lgkmcnt(2)
; DI void transpose_tile4(const float* src, int lds_, half_t* dst, int ldd, float* tile) {
;     ...
; #pragma unroll
;   for (int i = 0; i < 8; i++) {
;     int idx = i * 256 + tid, j = idx >> 9, r = idx & 511, kc = r >> 6, n = r & 63;
;     const float* t = tile + j * 4352 + kc * 8 * 68 + n;
;     h8 o;
; #pragma unroll
;     for (int u = 0; u < 8; u++) o[u] = (half_t)t[u * 68];
;     *(h8*)(dst + (size_t)(j * 64 + n) * ldd + kc * 8) = o;
;   }
;   __syncthreads();
	v_cvt_pk_f16_f32 v93, v92, v93
	v_cvt_pk_f16_f32 v92, v96, v97
	v_mul_lo_u32 v73, s47, v69
	v_mul_lo_u32 v9, s46, v9
	v_mad_u64_u32 v[96:97], s[28:29], s46, v69, 0
	v_add3_u32 v97, v97, v9, v73
	v_add_u32_e32 v9, 0x300, v7
	v_ashrrev_i32_e32 v69, 9, v9
	v_lshrrev_b32_e32 v9, 3, v9
	v_lshl_add_u64 v[96:97], v[96:97], 1, s[0:1]
	v_and_b32_e32 v9, 56, v9
	s_waitcnt lgkmcnt(0)
	v_cvt_pk_f16_f32 v95, v94, v95
	v_cvt_pk_f16_f32 v94, v98, v99
	v_lshl_add_u64 v[96:97], v[96:97], 0, v[20:21]
	v_mul_i32_i24_e32 v73, 0x4400, v69
	v_mul_u32_u24_e32 v75, 0x110, v9
	global_store_dwordx4 v[96:97], v[92:95], off
	v_add3_u32 v73, v73, v75, v8
	ds_read2_b32 v[96:97], v73 offset1:68
	ds_read2_b32 v[92:93], v73 offset0:136 offset1:204
	v_add_u32_e32 v73, 0x400, v73
	ds_read2_b32 v[98:99], v73 offset0:16 offset1:84
	ds_read2_b32 v[94:95], v73 offset0:152 offset1:220
	v_lshl_or_b32 v73, v69, 6, v6
	v_ashrrev_i32_e32 v69, 31, v69
	s_waitcnt lgkmcnt(2)
	v_cvt_pk_f16_f32 v93, v92, v93
	v_cvt_pk_f16_f32 v92, v96, v97
	v_mul_lo_u32 v75, s47, v73
	v_mul_lo_u32 v69, s46, v69
	v_mad_u64_u32 v[96:97], s[28:29], s46, v73, 0
	s_waitcnt lgkmcnt(0)
	v_cvt_pk_f16_f32 v95, v94, v95
	v_cvt_pk_f16_f32 v94, v98, v99
	v_add3_u32 v97, v97, v69, v75
	v_lshlrev_b32_e32 v98, 1, v9
	v_add_u32_e32 v9, 0x400, v7
	v_lshl_add_u64 v[96:97], v[96:97], 1, s[0:1]
	v_mov_b32_e32 v99, v21
	v_ashrrev_i32_e32 v9, 9, v9
	v_lshl_add_u64 v[96:97], v[96:97], 0, v[98:99]
	v_mul_i32_i24_e32 v69, 0x4400, v9
	global_store_dwordx4 v[96:97], v[92:95], off
	v_add3_u32 v69, v69, v71, v8
	ds_read2_b32 v[96:97], v69 offset1:68
	ds_read2_b32 v[92:93], v69 offset0:136 offset1:204
	v_add_u32_e32 v69, 0x400, v69
	ds_read2_b32 v[98:99], v69 offset0:16 offset1:84
	ds_read2_b32 v[94:95], v69 offset0:152 offset1:220
	v_lshl_or_b32 v69, v9, 6, v6
	v_ashrrev_i32_e32 v9, 31, v9
	s_waitcnt lgkmcnt(2)
	v_cvt_pk_f16_f32 v93, v92, v93
	v_cvt_pk_f16_f32 v92, v96, v97
	v_mul_lo_u32 v73, s47, v69
	v_mul_lo_u32 v9, s46, v9
	v_mad_u64_u32 v[96:97], s[28:29], s46, v69, 0
	v_add3_u32 v97, v97, v9, v73
	v_add_u32_e32 v9, 0x500, v7
	v_ashrrev_i32_e32 v69, 9, v9
	v_lshrrev_b32_e32 v9, 3, v9
	v_lshl_add_u64 v[96:97], v[96:97], 1, s[0:1]
	v_and_b32_e32 v9, 56, v9
	s_waitcnt lgkmcnt(0)
	v_cvt_pk_f16_f32 v95, v94, v95
	v_cvt_pk_f16_f32 v94, v98, v99
	v_lshl_add_u64 v[96:97], v[96:97], 0, v[20:21]
	v_mul_i32_i24_e32 v73, 0x4400, v69
	v_mul_u32_u24_e32 v75, 0x110, v9
	global_store_dwordx4 v[96:97], v[92:95], off
	v_add3_u32 v73, v73, v75, v8
	ds_read2_b32 v[96:97], v73 offset1:68
	ds_read2_b32 v[92:93], v73 offset0:136 offset1:204
	v_add_u32_e32 v73, 0x400, v73
	ds_read2_b32 v[98:99], v73 offset0:16 offset1:84
	ds_read2_b32 v[94:95], v73 offset0:152 offset1:220
	v_lshl_or_b32 v73, v69, 6, v6
	v_ashrrev_i32_e32 v69, 31, v69
	s_waitcnt lgkmcnt(2)
	v_cvt_pk_f16_f32 v93, v92, v93
	v_cvt_pk_f16_f32 v92, v96, v97
	v_mul_lo_u32 v75, s47, v73
	v_mul_lo_u32 v69, s46, v69
	v_mad_u64_u32 v[96:97], s[28:29], s46, v73, 0
	s_waitcnt lgkmcnt(0)
	v_cvt_pk_f16_f32 v95, v94, v95
	v_cvt_pk_f16_f32 v94, v98, v99
	v_add3_u32 v97, v97, v69, v75
	v_lshlrev_b32_e32 v98, 1, v9
	v_add_u32_e32 v9, 0x600, v7
	v_lshl_add_u64 v[96:97], v[96:97], 1, s[0:1]
	v_mov_b32_e32 v99, v21
	v_ashrrev_i32_e32 v9, 9, v9
	v_lshl_add_u64 v[96:97], v[96:97], 0, v[98:99]
	v_mul_i32_i24_e32 v69, 0x4400, v9
	global_store_dwordx4 v[96:97], v[92:95], off
	v_add3_u32 v69, v69, v71, v8
	ds_read2_b32 v[96:97], v69 offset1:68
	ds_read2_b32 v[92:93], v69 offset0:136 offset1:204
	v_add_u32_e32 v69, 0x400, v69
	ds_read2_b32 v[98:99], v69 offset0:16 offset1:84
	ds_read2_b32 v[94:95], v69 offset0:152 offset1:220
	v_lshl_or_b32 v69, v9, 6, v6
	v_ashrrev_i32_e32 v9, 31, v9
	s_waitcnt lgkmcnt(2)
	v_cvt_pk_f16_f32 v93, v92, v93
	v_cvt_pk_f16_f32 v92, v96, v97
	v_mul_lo_u32 v71, s47, v69
	v_mul_lo_u32 v9, s46, v9
	v_mad_u64_u32 v[96:97], s[28:29], s46, v69, 0
	v_add3_u32 v97, v97, v9, v71
	v_lshl_add_u64 v[96:97], v[96:97], 1, s[0:1]
	v_add_u32_e32 v7, 0x700, v7
	v_lshl_add_u64 v[96:97], v[96:97], 0, v[20:21]
	v_ashrrev_i32_e32 v20, 9, v7
	v_lshrrev_b32_e32 v7, 3, v7
	v_and_b32_e32 v69, 56, v7
	s_waitcnt lgkmcnt(0)
	v_cvt_pk_f16_f32 v95, v94, v95
	v_cvt_pk_f16_f32 v94, v98, v99
	v_mul_i32_i24_e32 v9, 0x4400, v20
	v_mul_u32_u24_e32 v7, 0x110, v69
	global_store_dwordx4 v[96:97], v[92:95], off
	v_add3_u32 v7, v9, v7, v8
	ds_read2_b32 v[8:9], v7 offset1:68
	ds_read2_b32 v[92:93], v7 offset0:136 offset1:204
	v_add_u32_e32 v7, 0x400, v7
	ds_read2_b32 v[96:97], v7 offset0:16 offset1:84
	ds_read2_b32 v[94:95], v7 offset0:152 offset1:220
	v_lshl_or_b32 v6, v20, 6, v6
	v_ashrrev_i32_e32 v7, 31, v20
	s_waitcnt lgkmcnt(2)
	v_cvt_pk_f16_f32 v93, v92, v93
	v_cvt_pk_f16_f32 v92, v8, v9
	v_mul_lo_u32 v8, s47, v6
	v_mul_lo_u32 v9, s46, v7
	v_mad_u64_u32 v[6:7], s[28:29], s46, v6, 0
	v_add3_u32 v7, v7, v9, v8
	v_lshl_add_u64 v[6:7], v[6:7], 1, s[0:1]
	v_lshlrev_b32_e32 v20, 1, v69
	s_waitcnt lgkmcnt(0)
	v_cvt_pk_f16_f32 v95, v94, v95
	v_cvt_pk_f16_f32 v94, v96, v97
	v_lshl_add_u64 v[6:7], v[6:7], 0, v[20:21]
	global_store_dwordx4 v[6:7], v[92:95], off
	s_barrier

; DI void phase0(const Params& P, char* smem) {
;     ...
;       const float* w = P.w_mod + ((size_t)l * 1024 + kq * 256) * 6144 + col0 + col;
; #pragma unroll 16
;       for (int k = 0; k < 256; k++) {
;         float wv = w[(size_t)k * 6144];
; #pragma unroll
;         for (int n = 0; n < 9; n++) acc[n] += scond[n * 1024 + kq * 256 + k] * wv;
;       }
.LBB0_108:
	v_lshl_add_u64 v[8:9], v[6:7], 0, s[48:49]
	s_mov_b64 s[100:101], 0x6000
	v_mov_b32_e32 v186, v8
	v_mov_b32_e32 v187, v9
	global_load_dword v188, v[8:9], off
	v_lshl_add_u64 v[186:187], v[186:187], 0, s[100:101]
	global_load_dword v189, v[186:187], off
	v_lshl_add_u64 v[186:187], v[186:187], 0, s[100:101]
	global_load_dword v190, v[186:187], off
	v_lshl_add_u64 v[186:187], v[186:187], 0, s[100:101]
	global_load_dword v191, v[186:187], off
	v_lshl_add_u64 v[186:187], v[186:187], 0, s[100:101]
	global_load_dword v192, v[186:187], off
	v_lshl_add_u64 v[186:187], v[186:187], 0, s[100:101]
	global_load_dword v193, v[186:187], off
	v_lshl_add_u64 v[186:187], v[186:187], 0, s[100:101]
	global_load_dword v194, v[186:187], off
	v_lshl_add_u64 v[186:187], v[186:187], 0, s[100:101]
	global_load_dword v195, v[186:187], off
	v_lshl_add_u64 v[186:187], v[186:187], 0, s[100:101]
	global_load_dword v196, v[186:187], off
	v_lshl_add_u64 v[186:187], v[186:187], 0, s[100:101]
	global_load_dword v197, v[186:187], off
	v_lshl_add_u64 v[186:187], v[186:187], 0, s[100:101]
	global_load_dword v198, v[186:187], off
	v_lshl_add_u64 v[186:187], v[186:187], 0, s[100:101]
	global_load_dword v199, v[186:187], off
	v_lshl_add_u64 v[186:187], v[186:187], 0, s[100:101]
	global_load_dword v200, v[186:187], off
	v_lshl_add_u64 v[186:187], v[186:187], 0, s[100:101]
	global_load_dword v201, v[186:187], off
	v_lshl_add_u64 v[186:187], v[186:187], 0, s[100:101]
	global_load_dword v202, v[186:187], off
	v_lshl_add_u64 v[186:187], v[186:187], 0, s[100:101]
	global_load_dword v203, v[186:187], off
	ds_read_b128 v[154:157], v69
	ds_read_b128 v[158:161], v69 offset:16
	ds_read_b128 v[126:129], v69 offset:32
	ds_read_b128 v[122:125], v69 offset:48
	ds_read_b128 v[132:135], v69 offset:4096
	s_waitcnt lgkmcnt(4)
	v_mov_b32_e32 v136, v154
	v_add_co_u32_e32 v152, vcc, s23, v8
	s_mov_b32 s28, 0xc000
	s_waitcnt lgkmcnt(0)
	v_mov_b32_e32 v137, v132
	v_addc_co_u32_e32 v153, vcc, 0, v9, vcc
	v_mov_b32_e32 v132, v155
	s_add_u32 s48, s48, 0x60000
	s_addc_u32 s49, s49, 0
	s_cmp_eq_u32 s48, 0x600000
	s_waitcnt vmcnt(15)
	v_mov_b32_e32 v20, v188
	v_pk_fma_f32 v[144:145], v[20:21], v[136:137], v[96:97] op_sel_hi:[0,1,1]
	ds_read_b128 v[162:165], v69 offset:8192
	ds_read_b128 v[136:139], v69 offset:12288
	s_waitcnt lgkmcnt(1)
	v_mov_b32_e32 v96, v162
	s_waitcnt lgkmcnt(0)
	v_mov_b32_e32 v97, v136
	v_pk_fma_f32 v[146:147], v[20:21], v[96:97], v[98:99] op_sel_hi:[0,1,1]
	ds_read_b128 v[166:169], v69 offset:16384
	ds_read_b128 v[96:99], v69 offset:20480
	v_mov_b32_e32 v136, v163
	s_waitcnt lgkmcnt(1)
	v_mov_b32_e32 v140, v166
	s_waitcnt lgkmcnt(0)
	v_mov_b32_e32 v141, v96
	v_pk_fma_f32 v[148:149], v[20:21], v[140:141], v[94:95] op_sel_hi:[0,1,1]
	ds_read_b128 v[174:177], v69 offset:24576
	ds_read_b128 v[140:143], v69 offset:28672
	v_mov_b32_e32 v96, v167
	s_waitcnt lgkmcnt(1)
	v_mov_b32_e32 v94, v174
	s_waitcnt lgkmcnt(0)
	v_mov_b32_e32 v95, v140
	v_pk_fma_f32 v[150:151], v[20:21], v[94:95], v[92:93] op_sel_hi:[0,1,1]
	ds_read_b128 v[92:95], v69 offset:32768
	v_mov_b32_e32 v140, v175
	s_waitcnt lgkmcnt(0)
	v_fmac_f32_e32 v71, v20, v92
	v_add_co_u32_e32 v92, vcc, s28, v8
	s_mov_b32 s28, 0x12000
	s_waitcnt vmcnt(14)
	v_mov_b32_e32 v20, v189
	v_fmac_f32_e32 v71, v20, v93
	v_addc_co_u32_e32 v93, vcc, 0, v9, vcc
	v_pk_fma_f32 v[132:133], v[20:21], v[132:133], v[144:145] op_sel_hi:[0,1,1]
	v_pk_fma_f32 v[136:137], v[20:21], v[136:137], v[146:147] op_sel_hi:[0,1,1]
	v_pk_fma_f32 v[96:97], v[20:21], v[96:97], v[148:149] op_sel_hi:[0,1,1]
	v_pk_fma_f32 v[140:141], v[20:21], v[140:141], v[150:151] op_sel_hi:[0,1,1]
	v_mov_b32_e32 v92, v156
	v_mov_b32_e32 v93, v134
	v_mov_b32_e32 v134, v157
	s_waitcnt vmcnt(13)
	v_mov_b32_e32 v20, v190
	v_pk_fma_f32 v[92:93], v[20:21], v[92:93], v[132:133] op_sel_hi:[0,1,1]
	v_mov_b32_e32 v132, v164
	v_mov_b32_e32 v133, v138
	v_pk_fma_f32 v[132:133], v[20:21], v[132:133], v[136:137] op_sel_hi:[0,1,1]
	v_mov_b32_e32 v136, v168
	v_mov_b32_e32 v137, v98
	v_pk_fma_f32 v[96:97], v[20:21], v[136:137], v[96:97] op_sel_hi:[0,1,1]
	v_mov_b32_e32 v136, v176
	v_mov_b32_e32 v137, v142
	v_pk_fma_f32 v[136:137], v[20:21], v[136:137], v[140:141] op_sel_hi:[0,1,1]
	v_add_co_u32_e32 v140, vcc, s28, v8
	v_fmac_f32_e32 v71, v20, v94
	s_nop 0
	v_addc_co_u32_e32 v141, vcc, 0, v9, vcc
	v_mov_b32_e32 v138, v165
	v_mov_b32_e32 v98, v169
	v_mov_b32_e32 v142, v177
	s_mov_b32 s28, 0x1e000
	s_waitcnt vmcnt(12)
	v_mov_b32_e32 v20, v191
	v_pk_fma_f32 v[134:135], v[20:21], v[134:135], v[92:93] op_sel_hi:[0,1,1]
	v_add_co_u32_e32 v92, vcc, s27, v8
	v_pk_fma_f32 v[132:133], v[20:21], v[138:139], v[132:133] op_sel_hi:[0,1,1]
	s_nop 0
	v_addc_co_u32_e32 v93, vcc, 0, v9, vcc
	v_pk_fma_f32 v[138:139], v[20:21], v[98:99], v[96:97] op_sel_hi:[0,1,1]
	v_pk_fma_f32 v[140:141], v[20:21], v[142:143], v[136:137] op_sel_hi:[0,1,1]
	v_fmac_f32_e32 v71, v20, v95
	ds_read_b128 v[92:95], v69 offset:4112
	v_mov_b32_e32 v96, v158
	v_add_co_u32_e32 v152, vcc, s28, v8
	s_mov_b32 s28, 0x24000
	s_waitcnt lgkmcnt(0)
	v_mov_b32_e32 v97, v92
	v_addc_co_u32_e32 v153, vcc, 0, v9, vcc
	v_mov_b32_e32 v92, v159
	s_waitcnt vmcnt(11)
	v_mov_b32_e32 v20, v192
	v_pk_fma_f32 v[144:145], v[20:21], v[96:97], v[134:135] op_sel_hi:[0,1,1]
	ds_read_b128 v[154:157], v69 offset:8208
	ds_read_b128 v[96:99], v69 offset:12304
	s_waitcnt lgkmcnt(1)
	v_mov_b32_e32 v134, v154
	s_waitcnt lgkmcnt(0)
	v_mov_b32_e32 v135, v96
	v_pk_fma_f32 v[146:147], v[20:21], v[134:135], v[132:133] op_sel_hi:[0,1,1]
	ds_read_b128 v[162:165], v69 offset:16400
	ds_read_b128 v[132:135], v69 offset:20496
	v_mov_b32_e32 v96, v155
	s_waitcnt lgkmcnt(1)
; DI void phase0(const Params& P, char* smem) {
;     ...
;       const float* w = P.w_mod + ((size_t)l * 1024 + kq * 256) * 6144 + col0 + col;
; #pragma unroll 16
;       for (int k = 0; k < 256; k++) {
;         float wv = w[(size_t)k * 6144];
; #pragma unroll
;         for (int n = 0; n < 9; n++) acc[n] += scond[n * 1024 + kq * 256 + k] * wv;
;       }
	v_mov_b32_e32 v136, v162
	s_waitcnt lgkmcnt(0)
	v_mov_b32_e32 v137, v132
	v_pk_fma_f32 v[148:149], v[20:21], v[136:137], v[138:139] op_sel_hi:[0,1,1]
	ds_read_b128 v[166:169], v69 offset:24592
	ds_read_b128 v[136:139], v69 offset:28688
	v_mov_b32_e32 v132, v163
	s_waitcnt lgkmcnt(1)
	v_mov_b32_e32 v142, v166
	s_waitcnt lgkmcnt(0)
	v_mov_b32_e32 v143, v136
	v_pk_fma_f32 v[150:151], v[20:21], v[142:143], v[140:141] op_sel_hi:[0,1,1]
	ds_read_b128 v[140:143], v69 offset:32784
	v_mov_b32_e32 v136, v167
	s_waitcnt lgkmcnt(0)
	v_fmac_f32_e32 v71, v20, v140
	v_add_co_u32_e32 v140, vcc, s28, v8
	s_mov_b32 s28, 0x2a000
	s_waitcnt vmcnt(10)
	v_mov_b32_e32 v20, v193
	v_fmac_f32_e32 v71, v20, v141
	v_addc_co_u32_e32 v141, vcc, 0, v9, vcc
	v_pk_fma_f32 v[92:93], v[20:21], v[92:93], v[144:145] op_sel_hi:[0,1,1]
	v_pk_fma_f32 v[96:97], v[20:21], v[96:97], v[146:147] op_sel_hi:[0,1,1]
	v_pk_fma_f32 v[132:133], v[20:21], v[132:133], v[148:149] op_sel_hi:[0,1,1]
	v_pk_fma_f32 v[136:137], v[20:21], v[136:137], v[150:151] op_sel_hi:[0,1,1]
	v_mov_b32_e32 v140, v160
	v_mov_b32_e32 v141, v94
	v_mov_b32_e32 v94, v161
	s_waitcnt vmcnt(9)
	v_mov_b32_e32 v20, v194
	v_pk_fma_f32 v[92:93], v[20:21], v[140:141], v[92:93] op_sel_hi:[0,1,1]
	v_mov_b32_e32 v140, v156
	v_mov_b32_e32 v141, v98
	v_pk_fma_f32 v[96:97], v[20:21], v[140:141], v[96:97] op_sel_hi:[0,1,1]
	v_mov_b32_e32 v140, v164
	v_mov_b32_e32 v141, v134
	v_pk_fma_f32 v[132:133], v[20:21], v[140:141], v[132:133] op_sel_hi:[0,1,1]
	v_mov_b32_e32 v140, v168
	v_mov_b32_e32 v141, v138
	v_pk_fma_f32 v[136:137], v[20:21], v[140:141], v[136:137] op_sel_hi:[0,1,1]
	v_add_co_u32_e32 v140, vcc, s28, v8
	v_fmac_f32_e32 v71, v20, v142
	s_nop 0
	v_addc_co_u32_e32 v141, vcc, 0, v9, vcc
	s_mov_b32 s28, 0x30000
	v_mov_b32_e32 v98, v157
	v_mov_b32_e32 v134, v165
	v_mov_b32_e32 v138, v169
	s_waitcnt vmcnt(8)
	v_mov_b32_e32 v20, v195
	v_pk_fma_f32 v[140:141], v[20:21], v[94:95], v[92:93] op_sel_hi:[0,1,1]
	v_add_co_u32_e32 v92, vcc, s28, v8
	v_pk_fma_f32 v[144:145], v[20:21], v[98:99], v[96:97] op_sel_hi:[0,1,1]
	s_nop 0
	v_addc_co_u32_e32 v93, vcc, 0, v9, vcc
	v_pk_fma_f32 v[146:147], v[20:21], v[134:135], v[132:133] op_sel_hi:[0,1,1]
	v_pk_fma_f32 v[148:149], v[20:21], v[138:139], v[136:137] op_sel_hi:[0,1,1]
	v_fmac_f32_e32 v71, v20, v143
	ds_read_b128 v[92:95], v69 offset:4128
	v_mov_b32_e32 v96, v126
	s_mov_b32 s28, 0x36000
	v_add_co_u32_e32 v152, vcc, s28, v8
	s_waitcnt lgkmcnt(0)
	v_mov_b32_e32 v97, v92
	v_addc_co_u32_e32 v153, vcc, 0, v9, vcc
	s_mov_b32 s28, 0x3c000
	v_mov_b32_e32 v92, v127
	s_waitcnt vmcnt(7)
	v_mov_b32_e32 v20, v196
	v_pk_fma_f32 v[150:151], v[20:21], v[96:97], v[140:141] op_sel_hi:[0,1,1]
	ds_read_b128 v[154:157], v69 offset:8224
	ds_read_b128 v[96:99], v69 offset:12320
	s_waitcnt lgkmcnt(1)
	v_mov_b32_e32 v132, v154
	s_waitcnt lgkmcnt(0)
	v_mov_b32_e32 v133, v96
	v_pk_fma_f32 v[144:145], v[20:21], v[132:133], v[144:145] op_sel_hi:[0,1,1]
	ds_read_b128 v[158:161], v69 offset:16416
	ds_read_b128 v[132:135], v69 offset:20512
	v_mov_b32_e32 v96, v155
	s_waitcnt lgkmcnt(1)
	v_mov_b32_e32 v136, v158
	s_waitcnt lgkmcnt(0)
	v_mov_b32_e32 v137, v132
	v_pk_fma_f32 v[146:147], v[20:21], v[136:137], v[146:147] op_sel_hi:[0,1,1]
	ds_read_b128 v[162:165], v69 offset:24608
	ds_read_b128 v[136:139], v69 offset:28704
	v_mov_b32_e32 v132, v159
	s_waitcnt lgkmcnt(1)
	v_mov_b32_e32 v140, v162
	s_waitcnt lgkmcnt(0)
	v_mov_b32_e32 v141, v136
	v_pk_fma_f32 v[148:149], v[20:21], v[140:141], v[148:149] op_sel_hi:[0,1,1]
	ds_read_b128 v[140:143], v69 offset:32800
	v_mov_b32_e32 v136, v163
	s_waitcnt lgkmcnt(0)
	v_fmac_f32_e32 v71, v20, v140
	s_waitcnt vmcnt(6)
	v_mov_b32_e32 v20, v197
	v_pk_fma_f32 v[126:127], v[20:21], v[132:133], v[146:147] op_sel_hi:[0,1,1]
	v_pk_fma_f32 v[132:133], v[20:21], v[136:137], v[148:149] op_sel_hi:[0,1,1]
	v_add_co_u32_e32 v136, vcc, s28, v8
	v_pk_fma_f32 v[92:93], v[20:21], v[92:93], v[150:151] op_sel_hi:[0,1,1]
	s_nop 0
	v_addc_co_u32_e32 v137, vcc, 0, v9, vcc
	v_pk_fma_f32 v[96:97], v[20:21], v[96:97], v[144:145] op_sel_hi:[0,1,1]
	v_fmac_f32_e32 v71, v20, v141
	v_mov_b32_e32 v136, v128
	v_mov_b32_e32 v137, v94
	s_mov_b32 s28, 0x42000
	v_mov_b32_e32 v94, v129
	s_waitcnt vmcnt(5)
	v_mov_b32_e32 v20, v198
	v_pk_fma_f32 v[92:93], v[20:21], v[136:137], v[92:93] op_sel_hi:[0,1,1]
	v_mov_b32_e32 v136, v156
	v_mov_b32_e32 v137, v98
	v_pk_fma_f32 v[96:97], v[20:21], v[136:137], v[96:97] op_sel_hi:[0,1,1]
	v_mov_b32_e32 v136, v160
	v_mov_b32_e32 v137, v134
	v_pk_fma_f32 v[126:127], v[20:21], v[136:137], v[126:127] op_sel_hi:[0,1,1]
	v_mov_b32_e32 v136, v164
	v_mov_b32_e32 v137, v138
	v_pk_fma_f32 v[132:133], v[20:21], v[136:137], v[132:133] op_sel_hi:[0,1,1]
	v_add_co_u32_e32 v136, vcc, s28, v8
	v_fmac_f32_e32 v71, v20, v142
	s_nop 0
	v_addc_co_u32_e32 v137, vcc, 0, v9, vcc
	s_mov_b32 s28, 0x48000
	v_mov_b32_e32 v98, v157
	v_mov_b32_e32 v134, v161
	v_mov_b32_e32 v138, v165
	s_waitcnt vmcnt(4)
; DI void phase0(const Params& P, char* smem) {
;     ...
; #pragma unroll 16
;       for (int k = 0; k < 256; k++) {
;         float wv = w[(size_t)k * 6144];
; #pragma unroll
;         for (int n = 0; n < 9; n++) acc[n] += scond[n * 1024 + kq * 256 + k] * wv;
;       }
; #pragma unroll
;       for (int n = 0; n < 9; n++) red[(kq * 9 + n) * 64 + col] = acc[n];
;       __syncthreads();
;       for (int idx = tid; idx < 576; idx += 256) {
;         int n = idx / 64, cc = idx % 64;
;         float s = red[(0 * 9 + n) * 64 + cc] + red[(1 * 9 + n) * 64 + cc] + red[(2 * 9 + n) * 64 + cc] + red[(3 * 9 + n) * 64 + cc];
;         P.mod[(size_t)(l * 9 + n) * 6144 + col0 + cc] = s + P.b_mod[l * 6144 + col0 + cc];
	v_mov_b32_e32 v20, v199
	v_pk_fma_f32 v[128:129], v[20:21], v[94:95], v[92:93] op_sel_hi:[0,1,1]
	v_add_co_u32_e32 v92, vcc, s28, v8
	v_pk_fma_f32 v[136:137], v[20:21], v[98:99], v[96:97] op_sel_hi:[0,1,1]
	s_nop 0
	v_addc_co_u32_e32 v93, vcc, 0, v9, vcc
	v_pk_fma_f32 v[134:135], v[20:21], v[134:135], v[126:127] op_sel_hi:[0,1,1]
	v_pk_fma_f32 v[138:139], v[20:21], v[138:139], v[132:133] op_sel_hi:[0,1,1]
	v_fmac_f32_e32 v71, v20, v143
	ds_read_b128 v[92:95], v69 offset:4144
	v_mov_b32_e32 v96, v122
	s_mov_b32 s28, 0x4e000
	v_add_co_u32_e32 v148, vcc, s28, v8
	s_waitcnt lgkmcnt(0)
	v_mov_b32_e32 v97, v92
	v_addc_co_u32_e32 v149, vcc, 0, v9, vcc
	s_mov_b32 s28, 0x54000
	v_mov_b32_e32 v92, v123
	s_waitcnt vmcnt(3)
	v_mov_b32_e32 v20, v200
	v_pk_fma_f32 v[140:141], v[20:21], v[96:97], v[128:129] op_sel_hi:[0,1,1]
	ds_read_b128 v[150:153], v69 offset:8240
	ds_read_b128 v[96:99], v69 offset:12336
	s_waitcnt lgkmcnt(1)
	v_mov_b32_e32 v126, v150
	s_waitcnt lgkmcnt(0)
	v_mov_b32_e32 v127, v96
	v_pk_fma_f32 v[142:143], v[20:21], v[126:127], v[136:137] op_sel_hi:[0,1,1]
	ds_read_b128 v[154:157], v69 offset:16432
	ds_read_b128 v[126:129], v69 offset:20528
	v_mov_b32_e32 v96, v151
	s_waitcnt lgkmcnt(1)
	v_mov_b32_e32 v132, v154
	s_waitcnt lgkmcnt(0)
	v_mov_b32_e32 v133, v126
	v_pk_fma_f32 v[144:145], v[20:21], v[132:133], v[134:135] op_sel_hi:[0,1,1]
	ds_read_b128 v[158:161], v69 offset:24624
	ds_read_b128 v[132:135], v69 offset:28720
	v_mov_b32_e32 v126, v155
	s_waitcnt lgkmcnt(1)
	v_mov_b32_e32 v136, v158
	s_waitcnt lgkmcnt(0)
	v_mov_b32_e32 v137, v132
	v_pk_fma_f32 v[146:147], v[20:21], v[136:137], v[138:139] op_sel_hi:[0,1,1]
	ds_read_b128 v[136:139], v69 offset:32816
	v_mov_b32_e32 v132, v159
	v_add_u32_e32 v69, 64, v69
	s_waitcnt lgkmcnt(0)
	v_fmac_f32_e32 v71, v20, v136
	s_waitcnt vmcnt(2)
	v_mov_b32_e32 v20, v201
	v_pk_fma_f32 v[122:123], v[20:21], v[126:127], v[144:145] op_sel_hi:[0,1,1]
	v_pk_fma_f32 v[126:127], v[20:21], v[132:133], v[146:147] op_sel_hi:[0,1,1]
	v_add_co_u32_e32 v132, vcc, s28, v8
	v_pk_fma_f32 v[92:93], v[20:21], v[92:93], v[140:141] op_sel_hi:[0,1,1]
	s_nop 0
	v_addc_co_u32_e32 v133, vcc, 0, v9, vcc
	v_pk_fma_f32 v[96:97], v[20:21], v[96:97], v[142:143] op_sel_hi:[0,1,1]
	v_fmac_f32_e32 v71, v20, v137
	s_mov_b32 s28, 0x5a000
	v_add_co_u32_e32 v8, vcc, s28, v8
	s_nop 1
	v_addc_co_u32_e32 v9, vcc, 0, v9, vcc
	v_mov_b32_e32 v132, v124
	v_mov_b32_e32 v133, v94
	v_mov_b32_e32 v94, v125
	s_waitcnt vmcnt(1)
	v_mov_b32_e32 v20, v202
	v_pk_fma_f32 v[92:93], v[20:21], v[132:133], v[92:93] op_sel_hi:[0,1,1]
	v_mov_b32_e32 v132, v152
	v_mov_b32_e32 v133, v98
	v_pk_fma_f32 v[132:133], v[20:21], v[132:133], v[96:97] op_sel_hi:[0,1,1]
	v_mov_b32_e32 v96, v156
	v_mov_b32_e32 v97, v128
	v_pk_fma_f32 v[122:123], v[20:21], v[96:97], v[122:123] op_sel_hi:[0,1,1]
	v_mov_b32_e32 v96, v160
	v_mov_b32_e32 v97, v134
	v_pk_fma_f32 v[126:127], v[20:21], v[96:97], v[126:127] op_sel_hi:[0,1,1]
	v_fmac_f32_e32 v71, v20, v138
	v_mov_b32_e32 v98, v153
	v_mov_b32_e32 v128, v157
	v_mov_b32_e32 v134, v161
	s_waitcnt vmcnt(0)
	v_mov_b32_e32 v8, v203
	v_pk_fma_f32 v[96:97], v[8:9], v[94:95], v[92:93] op_sel_hi:[0,1,1]
	v_pk_fma_f32 v[98:99], v[8:9], v[98:99], v[132:133] op_sel_hi:[0,1,1]
	v_pk_fma_f32 v[94:95], v[8:9], v[128:129], v[122:123] op_sel_hi:[0,1,1]
	v_pk_fma_f32 v[92:93], v[8:9], v[134:135], v[126:127] op_sel_hi:[0,1,1]
	v_fmac_f32_e32 v71, v8, v139
	s_cbranch_scc0 .LBB0_108
	v_readlane_b32 s4, v255, 42
	v_readlane_b32 s5, v255, 43
	ds_write2st64_b32 v118, v96, v97 offset0:144 offset1:145
	ds_write2st64_b32 v118, v98, v99 offset0:146 offset1:147
	ds_write2st64_b32 v118, v94, v95 offset0:148 offset1:149
	ds_write2st64_b32 v118, v92, v93 offset0:150 offset1:151
	ds_write_b32 v118, v71 offset:38912
	s_waitcnt lgkmcnt(0)
	s_barrier
	s_and_saveexec_b64 s[46:47], s[4:5]
	s_cbranch_execz .LBB0_112
	s_and_b64 s[28:29], s[0:1], exec
	s_cselect_b32 s28, 0x1800, 0
	s_add_i32 s28, s78, s28
	s_and_b64 s[0:1], s[0:1], exec
	s_cselect_b32 s29, 9, 0
	s_lshl_b64 s[0:1], s[78:79], 2
	v_readlane_b32 s48, v253, 59
	v_readlane_b32 s49, v253, 60
	s_add_u32 s0, s48, s0
	s_addc_u32 s1, s49, s1
	s_mov_b64 s[48:49], 0
	v_mov_b32_e32 v6, v107
	v_mov_b32_e32 v7, v12

; DI void phase0(const Params& P, char* smem) {
;     ...
;       int f = t - NT, l = f / 64, r = f % 64, kt = r / 4, g = r % 4;
;       float* cst = tile + 64 * 65; float* snt = cst + 64;
;       const float* src = P.w_in + (size_t)l * 1024 * 2304 + (size_t)kt * 64 * 2304 + g * 64;
;       { int n = tid & 63, kq = tid >> 6;
;         for (int i = 0; i < 16; i++) { int k = i * 4 + kq; tile[k * 65 + n] = src[(size_t)k * 2304 + n]; } }
;       if (tid < 64) { float s, c; sincospif((float)tid / 32.f, &s, &c); cst[tid] = c; snt[tid] = s; }
;       __syncthreads();
.LBB0_114:
	v_readlane_b32 s48, v253, 1
	s_add_i32 s0, s85, 0xffffe680
	v_readlane_b32 s52, v253, 5
	v_readlane_b32 s53, v253, 6
	s_lshr_b32 s46, s0, 6
	v_readlane_b32 s49, v253, 2
	v_readlane_b32 s50, v253, 3
	v_readlane_b32 s51, v253, 4
	s_mov_b64 s[76:77], s[52:53]
	s_bfe_u32 s29, s85, 0x40002
	s_mul_i32 s1, s46, 0x900000
	s_mov_b64 s[72:73], s[48:49]
	s_mul_hi_u32 s0, s46, 0x900000
	s_add_u32 s1, s72, s1
	s_addc_u32 s0, s73, s0
	s_mul_i32 s28, s29, 0x90000
	s_add_u32 s1, s1, s28
	s_addc_u32 s47, s0, 0
	s_lshl_b32 s0, s85, 6
	s_and_b32 s28, s0, 0xc0
	s_lshl_b32 s0, s28, 2
	s_add_u32 s0, s1, s0
	s_addc_u32 s1, s47, 0
	v_lshlrev_b32_e32 v20, 2, v16
	v_lshl_add_u64 v[6:7], s[0:1], 0, v[20:21]
	v_readlane_b32 s54, v253, 7
	v_readlane_b32 s55, v253, 8
	v_readlane_b32 s56, v253, 9
	v_readlane_b32 s57, v253, 10
	v_readlane_b32 s58, v253, 11
	v_readlane_b32 s59, v253, 12
	v_readlane_b32 s60, v253, 13
	v_readlane_b32 s61, v253, 14
	v_readlane_b32 s62, v253, 15
	v_readlane_b32 s63, v253, 16
	s_mov_b64 s[74:75], s[50:51]
	v_lshl_add_u64 v[186:187], v[6:7], 0, v[26:27]
	global_load_dword v188, v[186:187], off
	v_lshl_add_u64 v[186:187], v[6:7], 0, v[28:29]
	global_load_dword v189, v[186:187], off
	v_lshl_add_u64 v[186:187], v[6:7], 0, v[30:31]
	global_load_dword v190, v[186:187], off
	v_lshl_add_u64 v[186:187], v[6:7], 0, v[32:33]
	global_load_dword v191, v[186:187], off
	v_lshl_add_u64 v[186:187], v[6:7], 0, v[34:35]
	global_load_dword v192, v[186:187], off
	v_lshl_add_u64 v[186:187], v[6:7], 0, v[36:37]
	global_load_dword v193, v[186:187], off
	v_lshl_add_u64 v[186:187], v[6:7], 0, v[38:39]
	global_load_dword v194, v[186:187], off
	v_lshl_add_u64 v[186:187], v[6:7], 0, v[40:41]
	global_load_dword v195, v[186:187], off
	v_lshl_add_u64 v[186:187], v[6:7], 0, v[42:43]
	global_load_dword v196, v[186:187], off
	v_lshl_add_u64 v[186:187], v[6:7], 0, v[44:45]
	global_load_dword v197, v[186:187], off
	v_lshl_add_u64 v[186:187], v[6:7], 0, v[46:47]
	global_load_dword v198, v[186:187], off
	v_lshl_add_u64 v[186:187], v[6:7], 0, v[48:49]
	global_load_dword v199, v[186:187], off
	v_lshl_add_u64 v[186:187], v[6:7], 0, v[50:51]
	global_load_dword v200, v[186:187], off
	v_lshl_add_u64 v[186:187], v[6:7], 0, v[52:53]
	global_load_dword v201, v[186:187], off
	v_lshl_add_u64 v[186:187], v[6:7], 0, v[54:55]
	global_load_dword v202, v[186:187], off
	v_lshl_add_u64 v[186:187], v[6:7], 0, v[56:57]
	global_load_dword v203, v[186:187], off
	s_waitcnt vmcnt(15)
	ds_write_b32 v119, v188
	s_waitcnt vmcnt(14)
	ds_write_b32 v119, v189 offset:1040
	s_waitcnt vmcnt(13)
	ds_write_b32 v119, v190 offset:2080
	s_waitcnt vmcnt(12)
	ds_write_b32 v119, v191 offset:3120
	s_waitcnt vmcnt(11)
	ds_write_b32 v119, v192 offset:4160
	s_waitcnt vmcnt(10)
	ds_write_b32 v119, v193 offset:5200
	s_waitcnt vmcnt(9)
	ds_write_b32 v119, v194 offset:6240
	s_waitcnt vmcnt(8)
	ds_write_b32 v119, v195 offset:7280
	s_waitcnt vmcnt(7)
	ds_write_b32 v119, v196 offset:8320
	s_waitcnt vmcnt(6)
	ds_write_b32 v119, v197 offset:9360
	s_waitcnt vmcnt(5)
	ds_write_b32 v119, v198 offset:10400
	s_waitcnt vmcnt(4)
	ds_write_b32 v119, v199 offset:11440
	s_waitcnt vmcnt(3)
	ds_write_b32 v119, v200 offset:12480
	s_waitcnt vmcnt(2)
	ds_write_b32 v119, v201 offset:13520
	s_waitcnt vmcnt(1)
	ds_write_b32 v119, v202 offset:14560
	s_waitcnt vmcnt(0)
	ds_write_b32 v119, v203 offset:15600
	s_and_saveexec_b64 s[0:1], s[10:11]
	ds_write2st64_b32 v14, v23, v25 offset0:65 offset1:66
	s_or_b64 exec, exec, s[0:1]
	s_mul_hi_u32 s0, s46, 0x500000
	s_mul_i32 s46, s46, 0x500000
	s_add_u32 s1, s90, s46
	s_addc_u32 s46, s91, s0
	s_lshl_b32 s0, s29, 7
	s_add_u32 s0, s1, s0
	s_addc_u32 s1, s46, 0
	v_lshlrev_b32_e32 v20, 1, v16
	v_readlane_b32 s56, v255, 3
	v_lshl_add_u64 v[6:7], s[0:1], 0, v[20:21]
	s_or_b32 s0, s28, 0x100
	s_mov_b32 s1, 0
	v_mov_b32_e32 v20, v114
	v_mov_b32_e32 v69, v113
	v_mov_b32_e32 v71, v112
	v_mov_b32_e32 v73, v111
	v_mov_b32_e32 v75, v110
	v_mov_b32_e32 v92, v109
	v_mov_b32_e32 v93, v108
	v_mov_b32_e32 v94, v100
	v_readlane_b32 s58, v255, 5
	v_readlane_b32 s59, v255, 6
	v_readlane_b32 s62, v255, 9
	v_readlane_b32 s63, v255, 10
	v_readlane_b32 s64, v255, 11
	v_readlane_b32 s65, v255, 12
	v_readlane_b32 s66, v255, 13
	v_readlane_b32 s67, v255, 14
	s_mov_b32 s72, 0x3c800000
	s_mov_b32 s74, 0x3db504f3
	s_waitcnt lgkmcnt(0)
	s_barrier
	v_readlane_b32 s57, v255, 4
	v_readlane_b32 s60, v255, 7
	v_readlane_b32 s61, v255, 8
	v_readlane_b32 s68, v255, 15
	v_readlane_b32 s69, v255, 16
	v_readlane_b32 s70, v255, 17
	v_readlane_b32 s71, v255, 18
